# GU/QKV-type instances: first tile's row sums loaded ahead of the LDS-DMA prologue and converted while it is in flight (the header's wait had drained the second k-step's loads too)
# speedup vs baseline: 1.0148x; 1.0089x over previous
;     __device__ bool next(int i, Unit& u) const {
;         const long L = (long)i * G + c; if (L >= nwg) return false;
;         int wgid = (int)L; { const int q = nwg / NXCD, r = nwg % NXCD, xcd = wgid % NXCD, off = wgid / NXCD; wgid = (xcd < r ? xcd * (q + 1) : r * (q + 1) + (xcd - r) * q) + off; }
;         const int nig = WGM * nN, gid = wgid / nig, fm = gid * WGM, gsz = (nM - fm) < WGM ? (nM - fm) : WGM;
;         u.pm = fm + ((wgid % nig) % gsz); u.pn = (wgid % nig) / gsz; return true;
;     }
; template <class Epi, bool ALIGN_EPI>
; __device__ __forceinline__ void gemm_phase(LAS unsigned char* lds, const Gemm g, const StaticOrder& S, const Epi& E, const int tid) {
;     const int wid = __builtin_amdgcn_readfirstlane(tid >> 6), lane = tid & 63, wr = wid >> 2, wc = wid & 3, fr = lane & 15, fq = lane >> 4;
;     const int K = g.K, nt = K / BK;
;     unsigned voffA[2], voffB[2];
; #pragma unroll
;     for (int i = 0; i < 2; ++i) { int R, C; stage_rc(tid * 16 + i * 8192, R, C); const int Rb = Epi::PERM ? ((R & ~31) + perm32(R & 31)) : R;
;         voffA[i] = (unsigned)(R * g.lda + C) * 2u; voffB[i] = (unsigned)(Rb * g.ldb + C) * 2u; }
;     const size_t kstep = (size_t)(BK * 2);
;     const size_t hA = (size_t)HALF * g.lda * 2, hB = (size_t)HALF * g.ldb * 2, tA = 2 * hA, tB = 2 * hB;
;     const unsigned ldsw = (unsigned)wid * 1024u;
;     const int aoff = lds_byte(wr * 64 + fr, fq * 8), boff = lds_byte(wc * 32 + fr, fq * 8);
;     ...
;     Unit cur, nxt; int ui = 0;
;     if (!S.next(0, cur)) return;
;     f32x4 acc[2][2][4][2];
; #pragma unroll
;     for (int a = 0; a < 2; ++a)
; #pragma unroll
;         for (int b = 0; b < 2; ++b)
; #pragma unroll
;             for (int m = 0; m < 4; ++m)
; #pragma unroll
;                 for (int n = 0; n < 2; ++n) acc[a][b][m][n] = (f32x4){0.f, 0.f, 0.f, 0.f};
;     bf16x8 At[4][2], B0[2][2], B1[2][2];
;     const char* cA = (const char*)g.A + (size_t)cur.pm * tA + (size_t)cur.pn * g.apn * 2; const char* cB = (const char*)g.Bt + (size_t)cur.pn * tB;
;     PG8_STAGE(PG8_SB(0, 0), cB, voffB); PG8_STAGE(PG8_SB(0, 1), cB + hB, voffB); PG8_STAGE(PG8_SA(0, 0), cA, voffA); PG8_STAGE(PG8_SA(0, 1), cA + hA, voffA);
;     if (wr == 1) PG8_BAR;
;     PG8_WAIT_V(2); PG8_BAR;
;     PG8_STAGE(PG8_SB(1, 0), cB + kstep, voffB); PG8_STAGE(PG8_SA(1, 0), cA + kstep, voffA); PG8_STAGE(PG8_SB(1, 1), cB + hB + kstep, voffB);
.LBB0_294:
	s_cmp_ge_i32 s0, s38
	v_readfirstlane_b32 s8, v170
	s_cbranch_scc1 .LBB0_315
	v_lshlrev_b32_e32 v0, 4, v170
	s_waitcnt lgkmcnt(0)
	v_add_u32_e32 v1, 0x2000, v0
	v_ashrrev_i32_e32 v2, 31, v1
	v_lshrrev_b32_e32 v2, 22, v2
	v_add_u32_e32 v2, v1, v2
	v_ashrrev_i32_e32 v2, 10, v2
	v_mul_i32_i24_e32 v3, 0x400, v2
	v_sub_u32_e32 v1, v1, v3
	v_lshrrev_b32_e32 v3, 4, v1
	v_bitop3_b32 v1, v3, v1, 32 bitop3:0x6c
	v_ashrrev_i32_e32 v3, 31, v1
	v_lshrrev_b32_e32 v3, 26, v3
	v_add_u32_e32 v3, v1, v3
	s_waitcnt vmcnt(1)
	v_lshlrev_b32_e32 v5, 3, v2
	v_ashrrev_i32_e32 v4, 6, v3
	v_and_b32_e32 v5, -16, v5
	v_add_u32_e32 v5, v4, v5
	v_and_b32_e32 v3, 0xc0, v3
	v_and_b32_e32 v4, 3, v4
	s_mov_b32 s11, 0x7fffffe0
	v_lshrrev_b32_e32 v6, 2, v5
	v_lshlrev_b32_e32 v7, 1, v5
	v_sub_u32_e32 v1, v1, v3
	v_and_or_b32 v4, v5, s11, v4
	v_and_b32_e32 v6, 4, v6
	v_and_b32_e32 v7, 24, v7
	v_lshlrev_b32_e32 v2, 5, v2
	v_ashrrev_i16_sdwa v1, v235, sext(v1) dst_sel:DWORD dst_unused:UNUSED_PAD src0_sel:DWORD src1_sel:BYTE_0
	v_or3_b32 v4, v4, v6, v7
	v_and_b32_e32 v2, 32, v2
	v_bfe_i32 v3, v1, 0, 16
	v_mul_lo_u32 v4, s1, v4
	v_add_u32_e32 v1, v2, v3
	v_add_lshl_u32 v128, v4, v1, 1
	v_mul_lo_u32 v4, s25, v5
	v_add_lshl_u32 v130, v4, v1, 1
	v_bfe_i32 v1, v170, 27, 1
	v_lshrrev_b32_e32 v1, 22, v1
	v_add_u32_e32 v1, v0, v1
	v_and_b32_e32 v1, 0xfffffc00, v1
	v_sub_u32_e32 v0, v0, v1
	v_lshrrev_b32_e32 v1, 4, v0
	v_ashrrev_i32_e32 v6, 31, v170
	v_bitop3_b32 v0, v1, v0, 32 bitop3:0x6c
	v_lshrrev_b32_e32 v6, 26, v6
	v_ashrrev_i32_e32 v1, 31, v0
	v_add_u32_e32 v6, v170, v6
	v_lshrrev_b32_e32 v1, 26, v1
	v_ashrrev_i32_e32 v6, 6, v6
	v_add_u32_e32 v1, v0, v1
	v_lshlrev_b32_e32 v7, 3, v6
	v_ashrrev_i32_e32 v5, 6, v1
	v_and_b32_e32 v7, -16, v7
	v_add_u32_e32 v7, v5, v7
	v_and_b32_e32 v5, 3, v5
	s_ashr_i32 s47, s0, 31
	v_and_or_b32 v5, v7, s11, v5
	s_lshr_b32 s11, s47, 29
	s_add_i32 s11, s0, s11
	s_ashr_i32 s9, s8, 6
	s_lshl_b32 s94, s25, 8
	s_lshl_b32 s46, s7, 4
	s_ashr_i32 s39, s11, 3
	s_and_b32 s11, s11, -8
	s_ashr_i32 s10, s8, 8
	s_lshl_b32 s12, s1, 8
	s_lshl_b64 s[14:15], s[94:95], 1
	s_lshl_b32 s44, s1, 9
	s_lshl_b32 s45, s9, 10
	s_sub_i32 s11, s0, s11
	s_or_b32 s48, s46, 1
	s_cmp_lt_i32 s11, 0
	v_and_b32_e32 v1, 0xc0, v1
	s_cselect_b32 s40, s48, s46
	s_lshl_b32 s49, s7, 3
	v_lshrrev_b32_e32 v8, 2, v7
	v_lshlrev_b32_e32 v9, 1, v7
	v_sub_u32_e32 v0, v0, v1
	v_cvt_f32_u32_e32 v1, s49
	v_and_b32_e32 v8, 4, v8
	v_and_b32_e32 v9, 24, v9
	v_or3_b32 v5, v5, v8, v9
	v_mul_lo_u32 v8, s1, v5
	v_lshlrev_b32_e32 v5, 5, v6
	v_ashrrev_i16_sdwa v0, v235, sext(v0) dst_sel:DWORD dst_unused:UNUSED_PAD src0_sel:DWORD src1_sel:BYTE_0
	v_and_b32_e32 v5, 32, v5
	v_bfe_i32 v6, v0, 0, 16
	v_rcp_iflag_f32_e32 v1, v1
	v_add_u32_e32 v0, v5, v6
	v_mul_lo_u32 v7, s25, v7
	v_add_lshl_u32 v168, v8, v0, 1
	v_add_lshl_u32 v132, v7, v0, 1
	v_mov_b32_e32 v0, s11
	v_mul_i32_i24_e32 v0, s40, v0
	s_sub_i32 s41, 0, s49
	v_readfirstlane_b32 s11, v0
	v_mul_f32_e32 v0, 0x4f7ffffe, v1
	v_cvt_u32_f32_e32 v0, v0
	s_add_i32 s11, s11, s39
	s_abs_i32 s40, s11
	s_ashr_i32 s39, s11, 31
	v_readfirstlane_b32 s50, v0
	s_mul_i32 s41, s41, s50
	s_mul_hi_u32 s41, s50, s41
	s_add_i32 s50, s50, s41
	s_mul_hi_u32 s41, s40, s50
	s_mul_i32 s42, s41, s49
	s_sub_i32 s40, s40, s42
	s_add_i32 s42, s41, 1
	s_sub_i32 s43, s40, s49
	s_cmp_ge_u32 s40, s49
	s_cselect_b32 s41, s42, s41
	s_cselect_b32 s40, s43, s40
	s_add_i32 s42, s41, 1
	s_cmp_ge_u32 s40, s49
	s_cselect_b32 s40, s42, s41
	s_xor_b32 s40, s40, s39
	s_sub_i32 s39, s40, s39
	s_lshl_b32 s42, s39, 3
	s_sub_i32 s40, 0x80, s42
	s_min_i32 s43, s40, 8
	s_sext_i32_i16 s40, s43
	v_cvt_f32_i32_e32 v0, s40
	s_mul_i32 s39, s39, s49
	s_sub_i32 s11, s11, s39
	s_sext_i32_i16 s39, s11
	v_cvt_f32_i32_e32 v1, s39
	v_rcp_iflag_f32_e32 v8, v0
	s_xor_b32 s39, s39, s40
	s_ashr_i32 s39, s39, 30
	s_or_b32 s39, s39, 1
	v_mul_f32_e32 v8, v1, v8
	v_trunc_f32_e32 v8, v8
	v_fma_f32 v1, -v8, v0, v1
	v_cvt_i32_f32_e32 v8, v8
	v_cmp_ge_f32_e64 s[40:41], |v1|, |v0|
	s_and_b64 s[40:41], s[40:41], exec
	s_cselect_b32 s39, s39, 0
	v_readfirstlane_b32 s40, v8
	s_add_i32 s39, s40, s39
	s_mul_i32 s40, s39, s43
	s_sub_i32 s11, s11, s40
	s_sext_i32_i16 s11, s11
	s_add_i32 s64, s42, s11
	s_sext_i32_i16 s63, s39
	v_lshrrev_b32_e32 v194, 8, v170
	v_and_b32_e32 v195, 15, v170
	v_lshl_add_u32 v194, v194, 6, v195
	s_lshl_b32 s98, s64, 8
	v_add_u32_e32 v194, s98, v194
	v_lshlrev_b32_e32 v192, 3, v194
	v_mov_b32_e32 v193, 0
	v_lshl_add_u64 v[192:193], v[192:193], 0, s[26:27]
	global_load_dwordx2 v[176:177], v[192:193], off
	global_load_dwordx2 v[178:179], v[192:193], off offset:128
	global_load_dwordx2 v[180:181], v[192:193], off offset:256
	global_load_dwordx2 v[182:183], v[192:193], off offset:384
	global_load_dwordx2 v[184:185], v[192:193], off offset:1024
	global_load_dwordx2 v[186:187], v[192:193], off offset:1152
	global_load_dwordx2 v[188:189], v[192:193], off offset:1280
	global_load_dwordx2 v[190:191], v[192:193], off offset:1408
	s_ashr_i32 s11, s64, 31
	v_mov_b32_e32 v0, s63
	s_mul_i32 s11, s14, s11
	s_mul_hi_u32 s39, s14, s64
	v_mul_hi_i32_i24_e32 v9, s16, v0
	v_mul_i32_i24_e32 v8, s16, v0
	v_mul_hi_i32_i24_e32 v1, s44, v0
	v_mul_i32_i24_e32 v0, s44, v0
	s_add_i32 s11, s39, s11
	s_bfe_u32 s39, s25, 0x10017
	v_lshl_add_u64 v[144:145], s[22:23], 0, v[0:1]
	s_add_i32 s51, s45, 0
	s_mov_b32 s13, s95
	s_mul_i32 s39, s39, s64
	s_add_i32 m0, s51, 0x10000
	v_readfirstlane_b32 s42, v144
	v_readfirstlane_b32 s43, v145
	s_add_i32 s41, s11, s39
	s_mul_i32 s40, s14, s64
	v_lshl_add_u64 v[0:1], v[144:145], 0, s[12:13]
	v_lshl_add_u64 v[10:11], v[174:175], 0, s[40:41]
	v_readfirstlane_b32 s40, v0
	global_load_lds_dwordx4 v168, s[42:43]
	s_add_i32 m0, s51, 0x12000
	v_readfirstlane_b32 s41, v1
	global_load_lds_dwordx4 v128, s[42:43]
	s_add_i32 m0, s51, 0x14000
	v_lshl_add_u64 v[142:143], v[10:11], 0, v[8:9]
	s_add_i32 s52, s51, 0x2000
	s_nop 0
	global_load_lds_dwordx4 v168, s[40:41]
	s_add_i32 m0, s51, 0x16000
	v_lshl_add_u64 v[8:9], v[142:143], 0, s[94:95]
	global_load_lds_dwordx4 v128, s[40:41]
	v_readfirstlane_b32 s40, v142
	v_readfirstlane_b32 s41, v143
	s_mov_b32 m0, s51
	s_add_i32 s53, s51, 0x4000
	s_add_i32 s54, s51, 0x6000
	s_cmp_eq_u32 s10, 1
	s_nop 0
	global_load_lds_dwordx4 v132, s[40:41]
	s_mov_b32 m0, s52
	s_nop 0
	global_load_lds_dwordx4 v130, s[40:41]
	v_readfirstlane_b32 s40, v8
	v_readfirstlane_b32 s41, v9
	s_mov_b32 m0, s53
	s_nop 3
	global_load_lds_dwordx4 v132, s[40:41]
	s_mov_b32 m0, s54
	s_nop 0
	global_load_lds_dwordx4 v130, s[40:41]
	s_waitcnt vmcnt(8)
; #define PG8_STAGE(bufoff, gbase, voff) do { _Pragma("unroll") for (int _i = 0; _i < 2; ++_i) \
;         __builtin_amdgcn_global_load_lds((const unsigned*)((const char*)(gbase) + (voff)[_i]), (LAS unsigned*)(lds + (bufoff) + ldsw + _i * 8192), 16, 0, 0); } while (0)
; #define PG8_WAIT_V(n) asm volatile("s_waitcnt vmcnt(" #n ")" ::: "memory")
; #define PG8_BAR __builtin_amdgcn_s_barrier()
; __device__ __forceinline__ void load_rstd(float (&rsv)[2][4], const ssq_t* ssq, int row0) {
;     ...
; #pragma unroll
;     for (int ai = 0; ai < 2; ++ai)
; #pragma unroll
;         for (int m = 0; m < 4; ++m) rsv[ai][m] = __builtin_amdgcn_rsqf((float)t[ai][m] * (SSQ_INV / 1024.0f) + 1e-6f);
; template <class Epi, bool ALIGN_EPI>
; __device__ __forceinline__ void gemm_phase(LAS unsigned char* lds, const Gemm g, const StaticOrder& S, const Epi& E, const int tid) {
;     ...
;     if (wr == 1) PG8_BAR;
;     PG8_WAIT_V(2); PG8_BAR;
;     PG8_STAGE(PG8_SB(1, 0), cB + kstep, voffB); PG8_STAGE(PG8_SA(1, 0), cA + kstep, voffA); PG8_STAGE(PG8_SB(1, 1), cB + hB + kstep, voffB);
;     PG8_WAIT_V(6); PG8_BAR;
	v_ffbh_u32_e32 v194, v177
	v_min_u32_e32 v194, 32, v194
	v_lshlrev_b64 v[176:177], v194, v[176:177]
	v_min_u32_e32 v176, 1, v176
	v_or_b32_e32 v176, v177, v176
	v_cvt_f32_u32_e32 v176, v176
	v_sub_u32_e32 v194, 32, v194
	v_ldexp_f32 v176, v176, v194
	v_fmamk_f32 v176, v176, 0x30800000, v223
	v_rsq_f32_e32 v176, v176
	v_ffbh_u32_e32 v194, v179
	v_min_u32_e32 v194, 32, v194
	v_lshlrev_b64 v[178:179], v194, v[178:179]
	v_min_u32_e32 v178, 1, v178
	v_or_b32_e32 v178, v179, v178
	v_cvt_f32_u32_e32 v178, v178
	v_sub_u32_e32 v194, 32, v194
	v_ldexp_f32 v178, v178, v194
	v_fmamk_f32 v178, v178, 0x30800000, v223
	v_rsq_f32_e32 v178, v178
	v_ffbh_u32_e32 v194, v181
	v_min_u32_e32 v194, 32, v194
	v_lshlrev_b64 v[180:181], v194, v[180:181]
	v_min_u32_e32 v180, 1, v180
	v_or_b32_e32 v180, v181, v180
	v_cvt_f32_u32_e32 v180, v180
	v_sub_u32_e32 v194, 32, v194
	v_ldexp_f32 v180, v180, v194
	v_fmamk_f32 v180, v180, 0x30800000, v223
	v_rsq_f32_e32 v180, v180
	v_ffbh_u32_e32 v194, v183
	v_min_u32_e32 v194, 32, v194
	v_lshlrev_b64 v[182:183], v194, v[182:183]
	v_min_u32_e32 v182, 1, v182
	v_or_b32_e32 v182, v183, v182
	v_cvt_f32_u32_e32 v182, v182
	v_sub_u32_e32 v194, 32, v194
	v_ldexp_f32 v182, v182, v194
	v_fmamk_f32 v182, v182, 0x30800000, v223
	v_rsq_f32_e32 v182, v182
	v_ffbh_u32_e32 v194, v185
	v_min_u32_e32 v194, 32, v194
	v_lshlrev_b64 v[184:185], v194, v[184:185]
	v_min_u32_e32 v184, 1, v184
	v_or_b32_e32 v184, v185, v184
	v_cvt_f32_u32_e32 v184, v184
	v_sub_u32_e32 v194, 32, v194
	v_ldexp_f32 v184, v184, v194
	v_fmamk_f32 v184, v184, 0x30800000, v223
	v_rsq_f32_e32 v184, v184
	v_ffbh_u32_e32 v194, v187
	v_min_u32_e32 v194, 32, v194
	v_lshlrev_b64 v[186:187], v194, v[186:187]
	v_min_u32_e32 v186, 1, v186
	v_or_b32_e32 v186, v187, v186
	v_cvt_f32_u32_e32 v186, v186
	v_sub_u32_e32 v194, 32, v194
	v_ldexp_f32 v186, v186, v194
	v_fmamk_f32 v186, v186, 0x30800000, v223
	v_rsq_f32_e32 v186, v186
	v_ffbh_u32_e32 v194, v189
	v_min_u32_e32 v194, 32, v194
	v_lshlrev_b64 v[188:189], v194, v[188:189]
	v_min_u32_e32 v188, 1, v188
	v_or_b32_e32 v188, v189, v188
	v_cvt_f32_u32_e32 v188, v188
	v_sub_u32_e32 v194, 32, v194
	v_ldexp_f32 v188, v188, v194
	v_fmamk_f32 v188, v188, 0x30800000, v223
	v_rsq_f32_e32 v188, v188
	v_ffbh_u32_e32 v194, v191
	v_min_u32_e32 v194, 32, v194
	v_lshlrev_b64 v[190:191], v194, v[190:191]
	v_min_u32_e32 v190, 1, v190
	v_or_b32_e32 v190, v191, v190
	v_cvt_f32_u32_e32 v190, v190
	v_sub_u32_e32 v194, 32, v194
	v_ldexp_f32 v190, v190, v194
	v_fmamk_f32 v190, v190, 0x30800000, v223
	v_rsq_f32_e32 v190, v190
	v_mov_b32_e32 v172, v176
	v_mov_b32_e32 v173, v178
	v_mov_b32_e32 v236, v180
	v_mov_b32_e32 v237, v182
	v_mov_b32_e32 v238, v184
	v_mov_b32_e32 v239, v186
	v_mov_b32_e32 v230, v188
	v_mov_b32_e32 v231, v190
	v_mov_b32_e32 v254, s64
	s_cselect_b64 s[40:41], -1, 0
	s_cmp_lg_u32 s10, 1
	s_cbranch_scc1 .LBB0_297
	s_barrier
.LBB0_297:
	v_lshl_add_u64 v[8:9], v[144:145], 0, v[168:169]
	v_mov_b32_e32 v129, v169
	v_lshl_add_u64 v[10:11], v[144:145], 0, v[128:129]
	v_mov_b32_e32 v133, v169
	s_add_i32 m0, s51, 0x18000
	v_lshl_add_u64 v[8:9], v[8:9], 0, s[92:93]
	v_lshl_add_u64 v[14:15], v[142:143], 0, v[132:133]
	v_mov_b32_e32 v131, v169
	s_waitcnt vmcnt(2)
	s_barrier
	global_load_lds_dwordx4 v[8:9], off
	v_lshl_add_u64 v[8:9], v[10:11], 0, s[92:93]
	s_add_i32 m0, s51, 0x1a000
	s_add_i32 s56, s51, 0x8000
	v_lshl_add_u64 v[16:17], v[142:143], 0, v[130:131]
	global_load_lds_dwordx4 v[8:9], off
	v_lshl_add_u64 v[8:9], v[14:15], 0, s[92:93]
	s_mov_b32 m0, s56
	s_add_i32 s57, s51, 0xa000
	v_lshl_add_u64 v[12:13], v[0:1], 0, v[168:169]
	global_load_lds_dwordx4 v[8:9], off
	v_lshl_add_u64 v[8:9], v[16:17], 0, s[92:93]
	s_mov_b32 m0, s57
	v_lshl_add_u64 v[0:1], v[0:1], 0, v[128:129]
	global_load_lds_dwordx4 v[8:9], off
	s_add_i32 m0, s51, 0x1c000
	v_lshl_add_u64 v[8:9], v[12:13], 0, s[92:93]
	global_load_lds_dwordx4 v[8:9], off
	v_lshl_add_u64 v[0:1], v[0:1], 0, s[92:93]
	s_add_i32 m0, s51, 0x1e000
	v_and_b32_e32 v18, 15, v170
	global_load_lds_dwordx4 v[0:1], off
	v_add_u32_e32 v0, v7, v5
	s_lshr_b32 s55, s1, 6
	v_and_b32_e32 v19, 48, v170
	v_lshlrev_b32_e32 v18, 6, v18
	v_lshlrev_b32_e32 v21, 2, v170
	s_lshl_b32 s9, s9, 12
	v_add_lshl_u32 v0, v0, v6, 1
	v_mov_b32_e32 v1, v169
	v_or_b32_e32 v20, v18, v19
	s_lshl_b32 s10, s10, 13
	v_and_b32_e32 v21, 32, v21
	s_and_b32 s9, s9, 0x3000
	s_waitcnt vmcnt(6)
	s_add_i32 s58, s55, -2
	v_lshl_add_u64 v[134:135], s[94:95], 0, v[0:1]
	v_add_u32_e32 v0, v4, v2
	v_bitop3_b32 v18, v18, v21, v19 bitop3:0x36
	v_bitop3_b32 v19, s10, v20, v21 bitop3:0xf6
	s_cmpk_lt_u32 s8, 0x100
	v_add_lshl_u32 v0, v0, v3, 1
	v_or_b32_e32 v151, s9, v18
	s_cselect_b64 s[42:43], -1, 0
	s_ashr_i32 s59, s6, 31
	s_mov_b32 s39, s95
	v_lshl_add_u64 v[136:137], s[94:95], 0, v[0:1]
	s_mov_b32 s60, 0
	v_add_u32_e32 v153, 0, v19
	s_barrier
	s_mov_b32 s101, 0
	s_branch .LBB0_300

;     __device__ bool next(int i, Unit& u) const {
;         const long L = (long)i * G + c; if (L >= nwg) return false;
;         int wgid = (int)L; { const int q = nwg / NXCD, r = nwg % NXCD, xcd = wgid % NXCD, off = wgid / NXCD; wgid = (xcd < r ? xcd * (q + 1) : r * (q + 1) + (xcd - r) * q) + off; }
;         const int nig = WGM * nN, gid = wgid / nig, fm = gid * WGM, gsz = (nM - fm) < WGM ? (nM - fm) : WGM;
;         u.pm = fm + ((wgid % nig) % gsz); u.pn = (wgid % nig) / gsz; return true;
;     }
; template <class Epi, bool ALIGN_EPI>
; __device__ __forceinline__ void gemm_phase(LAS unsigned char* lds, const Gemm g, const StaticOrder& S, const Epi& E, const int tid) {
;     const int wid = __builtin_amdgcn_readfirstlane(tid >> 6), lane = tid & 63, wr = wid >> 2, wc = wid & 3, fr = lane & 15, fq = lane >> 4;
;     const int K = g.K, nt = K / BK;
;     unsigned voffA[2], voffB[2];
; #pragma unroll
;     for (int i = 0; i < 2; ++i) { int R, C; stage_rc(tid * 16 + i * 8192, R, C); const int Rb = Epi::PERM ? ((R & ~31) + perm32(R & 31)) : R;
;         voffA[i] = (unsigned)(R * g.lda + C) * 2u; voffB[i] = (unsigned)(Rb * g.ldb + C) * 2u; }
;     const size_t kstep = (size_t)(BK * 2);
;     const size_t hA = (size_t)HALF * g.lda * 2, hB = (size_t)HALF * g.ldb * 2, tA = 2 * hA, tB = 2 * hB;
;     const unsigned ldsw = (unsigned)wid * 1024u;
;     const int aoff = lds_byte(wr * 64 + fr, fq * 8), boff = lds_byte(wc * 32 + fr, fq * 8);
;     ...
;     Unit cur, nxt; int ui = 0;
;     if (!S.next(0, cur)) return;
;     f32x4 acc[2][2][4][2];
; #pragma unroll
;     for (int a = 0; a < 2; ++a)
; #pragma unroll
;         for (int b = 0; b < 2; ++b)
; #pragma unroll
;             for (int m = 0; m < 4; ++m)
; #pragma unroll
;                 for (int n = 0; n < 2; ++n) acc[a][b][m][n] = (f32x4){0.f, 0.f, 0.f, 0.f};
;     bf16x8 At[4][2], B0[2][2], B1[2][2];
;     const char* cA = (const char*)g.A + (size_t)cur.pm * tA + (size_t)cur.pn * g.apn * 2; const char* cB = (const char*)g.Bt + (size_t)cur.pn * tB;
;     PG8_STAGE(PG8_SB(0, 0), cB, voffB); PG8_STAGE(PG8_SB(0, 1), cB + hB, voffB); PG8_STAGE(PG8_SA(0, 0), cA, voffA); PG8_STAGE(PG8_SA(0, 1), cA + hA, voffA);
;     if (wr == 1) PG8_BAR;
;     PG8_WAIT_V(2); PG8_BAR;
;     PG8_STAGE(PG8_SB(1, 0), cB + kstep, voffB); PG8_STAGE(PG8_SA(1, 0), cA + kstep, voffA); PG8_STAGE(PG8_SB(1, 1), cB + hB + kstep, voffB);
.LBB0_339:
	s_andn2_b64 vcc, exec, s[10:11]
	s_cbranch_vccnz .LBB0_361
	s_cmp_ge_i32 s0, s38
	v_readfirstlane_b32 s8, v170
	s_cbranch_scc1 .LBB0_361
	v_lshlrev_b32_e32 v0, 4, v170
	s_waitcnt lgkmcnt(0)
	v_add_u32_e32 v1, 0x2000, v0
	v_ashrrev_i32_e32 v2, 31, v1
	v_lshrrev_b32_e32 v2, 22, v2
	v_add_u32_e32 v2, v1, v2
	v_ashrrev_i32_e32 v2, 10, v2
	v_mul_i32_i24_e32 v3, 0x400, v2
	v_sub_u32_e32 v1, v1, v3
	v_lshrrev_b32_e32 v3, 4, v1
	v_bitop3_b32 v1, v3, v1, 32 bitop3:0x6c
	v_ashrrev_i32_e32 v3, 31, v1
	v_lshrrev_b32_e32 v3, 26, v3
	v_add_u32_e32 v3, v1, v3
	s_waitcnt vmcnt(1)
	v_lshlrev_b32_e32 v5, 3, v2
	v_ashrrev_i32_e32 v4, 6, v3
	v_and_b32_e32 v5, -16, v5
	v_add_u32_e32 v5, v4, v5
	v_and_b32_e32 v3, 0xc0, v3
	v_and_b32_e32 v4, 3, v4
	s_mov_b32 s11, 0x7fffffe0
	v_lshrrev_b32_e32 v6, 2, v5
	v_lshlrev_b32_e32 v7, 1, v5
	v_sub_u32_e32 v1, v1, v3
	v_and_or_b32 v4, v5, s11, v4
	v_and_b32_e32 v6, 4, v6
	v_and_b32_e32 v7, 24, v7
	v_lshlrev_b32_e32 v2, 5, v2
	v_ashrrev_i16_sdwa v1, v235, sext(v1) dst_sel:DWORD dst_unused:UNUSED_PAD src0_sel:DWORD src1_sel:BYTE_0
	v_or3_b32 v4, v4, v6, v7
	v_and_b32_e32 v2, 32, v2
	v_bfe_i32 v3, v1, 0, 16
	v_mul_lo_u32 v4, s1, v4
	v_add_u32_e32 v1, v2, v3
	v_add_lshl_u32 v128, v4, v1, 1
	v_mul_lo_u32 v4, s25, v5
	v_add_lshl_u32 v130, v4, v1, 1
	v_bfe_i32 v1, v170, 27, 1
	v_lshrrev_b32_e32 v1, 22, v1
	v_add_u32_e32 v1, v0, v1
	v_and_b32_e32 v1, 0xfffffc00, v1
	v_sub_u32_e32 v0, v0, v1
	v_lshrrev_b32_e32 v1, 4, v0
	v_ashrrev_i32_e32 v6, 31, v170
	v_bitop3_b32 v0, v1, v0, 32 bitop3:0x6c
	v_lshrrev_b32_e32 v6, 26, v6
	v_ashrrev_i32_e32 v1, 31, v0
	v_add_u32_e32 v6, v170, v6
	v_lshrrev_b32_e32 v1, 26, v1
	v_ashrrev_i32_e32 v6, 6, v6
	v_add_u32_e32 v1, v0, v1
	v_lshlrev_b32_e32 v7, 3, v6
	v_ashrrev_i32_e32 v5, 6, v1
	v_and_b32_e32 v7, -16, v7
	v_add_u32_e32 v7, v5, v7
	v_and_b32_e32 v5, 3, v5
	s_ashr_i32 s47, s0, 31
	v_and_or_b32 v5, v7, s11, v5
	s_lshr_b32 s11, s47, 29
	s_add_i32 s11, s0, s11
	s_ashr_i32 s9, s8, 6
	s_lshl_b32 s94, s25, 8
	s_lshl_b32 s46, s7, 4
	s_ashr_i32 s39, s11, 3
	s_and_b32 s11, s11, -8
	s_ashr_i32 s10, s8, 8
	s_lshl_b32 s12, s1, 8
	s_lshl_b64 s[14:15], s[94:95], 1
	s_lshl_b32 s44, s1, 9
	s_lshl_b32 s45, s9, 10
	s_sub_i32 s11, s0, s11
	s_or_b32 s48, s46, 1
	s_cmp_lt_i32 s11, 0
	v_and_b32_e32 v1, 0xc0, v1
	s_cselect_b32 s40, s48, s46
	s_lshl_b32 s7, s7, 3
	v_lshrrev_b32_e32 v8, 2, v7
	v_lshlrev_b32_e32 v9, 1, v7
	v_sub_u32_e32 v0, v0, v1
	v_cvt_f32_u32_e32 v1, s7
	v_and_b32_e32 v8, 4, v8
	v_and_b32_e32 v9, 24, v9
	v_or3_b32 v5, v5, v8, v9
	v_mul_lo_u32 v8, s1, v5
	v_lshlrev_b32_e32 v5, 5, v6
	v_ashrrev_i16_sdwa v0, v235, sext(v0) dst_sel:DWORD dst_unused:UNUSED_PAD src0_sel:DWORD src1_sel:BYTE_0
	v_and_b32_e32 v5, 32, v5
	v_bfe_i32 v6, v0, 0, 16
	v_rcp_iflag_f32_e32 v1, v1
	v_add_u32_e32 v0, v5, v6
	v_mul_lo_u32 v7, s25, v7
	v_add_lshl_u32 v168, v8, v0, 1
	v_add_lshl_u32 v132, v7, v0, 1
	v_mov_b32_e32 v0, s11
	v_mul_i32_i24_e32 v0, s40, v0
	s_sub_i32 s41, 0, s7
	v_readfirstlane_b32 s11, v0
	v_mul_f32_e32 v0, 0x4f7ffffe, v1
	v_cvt_u32_f32_e32 v0, v0
	s_add_i32 s11, s11, s39
	s_abs_i32 s40, s11
	s_ashr_i32 s39, s11, 31
	v_readfirstlane_b32 s49, v0
	s_mul_i32 s41, s41, s49
	s_mul_hi_u32 s41, s49, s41
	s_add_i32 s49, s49, s41
	s_mul_hi_u32 s41, s40, s49
	s_mul_i32 s42, s41, s7
	s_sub_i32 s40, s40, s42
	s_add_i32 s42, s41, 1
	s_sub_i32 s43, s40, s7
	s_cmp_ge_u32 s40, s7
	s_cselect_b32 s41, s42, s41
	s_cselect_b32 s40, s43, s40
	s_add_i32 s42, s41, 1
	s_cmp_ge_u32 s40, s7
	s_cselect_b32 s40, s42, s41
	s_xor_b32 s40, s40, s39
	s_sub_i32 s39, s40, s39
	s_lshl_b32 s42, s39, 3
	s_sub_i32 s40, 0x80, s42
	s_min_i32 s43, s40, 8
	s_sext_i32_i16 s40, s43
	v_cvt_f32_i32_e32 v0, s40
	s_mul_i32 s39, s39, s7
	s_sub_i32 s11, s11, s39
	s_sext_i32_i16 s39, s11
	v_cvt_f32_i32_e32 v1, s39
	v_rcp_iflag_f32_e32 v8, v0
	s_xor_b32 s39, s39, s40
	s_ashr_i32 s39, s39, 30
	s_or_b32 s39, s39, 1
	v_mul_f32_e32 v8, v1, v8
	v_trunc_f32_e32 v8, v8
	v_fma_f32 v1, -v8, v0, v1
	v_cvt_i32_f32_e32 v8, v8
	v_cmp_ge_f32_e64 s[40:41], |v1|, |v0|
	s_and_b64 s[40:41], s[40:41], exec
	s_cselect_b32 s39, s39, 0
	v_readfirstlane_b32 s40, v8
	s_add_i32 s39, s40, s39
	s_mul_i32 s40, s39, s43
	s_sub_i32 s11, s11, s40
	s_sext_i32_i16 s11, s11
	s_add_i32 s61, s42, s11
	s_sext_i32_i16 s60, s39
	v_lshrrev_b32_e32 v194, 8, v170
	v_and_b32_e32 v195, 15, v170
	v_lshl_add_u32 v194, v194, 6, v195
	s_lshl_b32 s98, s61, 8
	v_add_u32_e32 v194, s98, v194
	v_lshlrev_b32_e32 v192, 3, v194
	v_mov_b32_e32 v193, 0
	v_lshl_add_u64 v[192:193], v[192:193], 0, s[26:27]
	global_load_dwordx2 v[176:177], v[192:193], off
	global_load_dwordx2 v[178:179], v[192:193], off offset:128
	global_load_dwordx2 v[180:181], v[192:193], off offset:256
	global_load_dwordx2 v[182:183], v[192:193], off offset:384
	global_load_dwordx2 v[184:185], v[192:193], off offset:1024
	global_load_dwordx2 v[186:187], v[192:193], off offset:1152
	global_load_dwordx2 v[188:189], v[192:193], off offset:1280
	global_load_dwordx2 v[190:191], v[192:193], off offset:1408
	s_ashr_i32 s11, s61, 31
	s_mul_i32 s11, s14, s11
	s_mul_hi_u32 s39, s14, s61
	s_bfe_u32 s25, s25, 0x10017
	v_mov_b32_e32 v0, s60
	s_add_i32 s11, s39, s11
	s_mul_i32 s25, s25, s61
	v_mul_hi_i32_i24_e32 v9, s16, v0
	v_mul_i32_i24_e32 v8, s16, v0
	v_mul_hi_i32_i24_e32 v1, s44, v0
	v_mul_i32_i24_e32 v0, s44, v0
	s_add_i32 s41, s11, s25
	v_lshl_add_u64 v[144:145], s[22:23], 0, v[0:1]
	s_add_i32 s25, s45, 0
	s_mov_b32 s13, s95
	s_add_i32 m0, s25, 0x10000
	v_readfirstlane_b32 s42, v144
	v_readfirstlane_b32 s43, v145
	s_mul_i32 s40, s14, s61
	v_lshl_add_u64 v[0:1], v[144:145], 0, s[12:13]
	v_lshl_add_u64 v[10:11], v[174:175], 0, s[40:41]
	v_readfirstlane_b32 s40, v0
	v_readfirstlane_b32 s41, v1
	global_load_lds_dwordx4 v168, s[42:43]
	s_add_i32 m0, s25, 0x12000
	v_lshl_add_u64 v[142:143], v[10:11], 0, v[8:9]
	global_load_lds_dwordx4 v128, s[42:43]
	s_add_i32 m0, s25, 0x14000
	s_add_i32 s50, s25, 0x2000
	global_load_lds_dwordx4 v168, s[40:41]
	s_add_i32 m0, s25, 0x16000
	v_lshl_add_u64 v[8:9], v[142:143], 0, s[94:95]
	global_load_lds_dwordx4 v128, s[40:41]
	v_readfirstlane_b32 s40, v142
	v_readfirstlane_b32 s41, v143
	s_mov_b32 m0, s25
	s_add_i32 s51, s25, 0x4000
	s_add_i32 s52, s25, 0x6000
	s_cmp_eq_u32 s10, 1
	s_nop 0
	global_load_lds_dwordx4 v132, s[40:41]
	s_mov_b32 m0, s50
	s_nop 0
	global_load_lds_dwordx4 v130, s[40:41]
	v_readfirstlane_b32 s40, v8
	v_readfirstlane_b32 s41, v9
	s_mov_b32 m0, s51
	s_nop 3
	global_load_lds_dwordx4 v132, s[40:41]
	s_mov_b32 m0, s52
	s_nop 0
	global_load_lds_dwordx4 v130, s[40:41]
	s_waitcnt vmcnt(8)
; #define PG8_STAGE(bufoff, gbase, voff) do { _Pragma("unroll") for (int _i = 0; _i < 2; ++_i) \
;         __builtin_amdgcn_global_load_lds((const unsigned*)((const char*)(gbase) + (voff)[_i]), (LAS unsigned*)(lds + (bufoff) + ldsw + _i * 8192), 16, 0, 0); } while (0)
; #define PG8_WAIT_V(n) asm volatile("s_waitcnt vmcnt(" #n ")" ::: "memory")
; #define PG8_BAR __builtin_amdgcn_s_barrier()
; __device__ __forceinline__ void load_rstd(float (&rsv)[2][4], const ssq_t* ssq, int row0) {
;     ...
; #pragma unroll
;     for (int ai = 0; ai < 2; ++ai)
; #pragma unroll
;         for (int m = 0; m < 4; ++m) rsv[ai][m] = __builtin_amdgcn_rsqf((float)t[ai][m] * (SSQ_INV / 1024.0f) + 1e-6f);
; template <class Epi, bool ALIGN_EPI>
; __device__ __forceinline__ void gemm_phase(LAS unsigned char* lds, const Gemm g, const StaticOrder& S, const Epi& E, const int tid) {
;     ...
;     if (wr == 1) PG8_BAR;
;     PG8_WAIT_V(2); PG8_BAR;
;     PG8_STAGE(PG8_SB(1, 0), cB + kstep, voffB); PG8_STAGE(PG8_SA(1, 0), cA + kstep, voffA); PG8_STAGE(PG8_SB(1, 1), cB + hB + kstep, voffB);
;     PG8_WAIT_V(6); PG8_BAR;
	v_ffbh_u32_e32 v194, v177
	v_min_u32_e32 v194, 32, v194
	v_lshlrev_b64 v[176:177], v194, v[176:177]
	v_min_u32_e32 v176, 1, v176
	v_or_b32_e32 v176, v177, v176
	v_cvt_f32_u32_e32 v176, v176
	v_sub_u32_e32 v194, 32, v194
	v_ldexp_f32 v176, v176, v194
	v_fmamk_f32 v176, v176, 0x30800000, v223
	v_rsq_f32_e32 v176, v176
	v_ffbh_u32_e32 v194, v179
	v_min_u32_e32 v194, 32, v194
	v_lshlrev_b64 v[178:179], v194, v[178:179]
	v_min_u32_e32 v178, 1, v178
	v_or_b32_e32 v178, v179, v178
	v_cvt_f32_u32_e32 v178, v178
	v_sub_u32_e32 v194, 32, v194
	v_ldexp_f32 v178, v178, v194
	v_fmamk_f32 v178, v178, 0x30800000, v223
	v_rsq_f32_e32 v178, v178
	v_ffbh_u32_e32 v194, v181
	v_min_u32_e32 v194, 32, v194
	v_lshlrev_b64 v[180:181], v194, v[180:181]
	v_min_u32_e32 v180, 1, v180
	v_or_b32_e32 v180, v181, v180
	v_cvt_f32_u32_e32 v180, v180
	v_sub_u32_e32 v194, 32, v194
	v_ldexp_f32 v180, v180, v194
	v_fmamk_f32 v180, v180, 0x30800000, v223
	v_rsq_f32_e32 v180, v180
	v_ffbh_u32_e32 v194, v183
	v_min_u32_e32 v194, 32, v194
	v_lshlrev_b64 v[182:183], v194, v[182:183]
	v_min_u32_e32 v182, 1, v182
	v_or_b32_e32 v182, v183, v182
	v_cvt_f32_u32_e32 v182, v182
	v_sub_u32_e32 v194, 32, v194
	v_ldexp_f32 v182, v182, v194
	v_fmamk_f32 v182, v182, 0x30800000, v223
	v_rsq_f32_e32 v182, v182
	v_ffbh_u32_e32 v194, v185
	v_min_u32_e32 v194, 32, v194
	v_lshlrev_b64 v[184:185], v194, v[184:185]
	v_min_u32_e32 v184, 1, v184
	v_or_b32_e32 v184, v185, v184
	v_cvt_f32_u32_e32 v184, v184
	v_sub_u32_e32 v194, 32, v194
	v_ldexp_f32 v184, v184, v194
	v_fmamk_f32 v184, v184, 0x30800000, v223
	v_rsq_f32_e32 v184, v184
	v_ffbh_u32_e32 v194, v187
	v_min_u32_e32 v194, 32, v194
	v_lshlrev_b64 v[186:187], v194, v[186:187]
	v_min_u32_e32 v186, 1, v186
	v_or_b32_e32 v186, v187, v186
	v_cvt_f32_u32_e32 v186, v186
	v_sub_u32_e32 v194, 32, v194
	v_ldexp_f32 v186, v186, v194
	v_fmamk_f32 v186, v186, 0x30800000, v223
	v_rsq_f32_e32 v186, v186
	v_ffbh_u32_e32 v194, v189
	v_min_u32_e32 v194, 32, v194
	v_lshlrev_b64 v[188:189], v194, v[188:189]
	v_min_u32_e32 v188, 1, v188
	v_or_b32_e32 v188, v189, v188
	v_cvt_f32_u32_e32 v188, v188
	v_sub_u32_e32 v194, 32, v194
	v_ldexp_f32 v188, v188, v194
	v_fmamk_f32 v188, v188, 0x30800000, v223
	v_rsq_f32_e32 v188, v188
	v_ffbh_u32_e32 v194, v191
	v_min_u32_e32 v194, 32, v194
	v_lshlrev_b64 v[190:191], v194, v[190:191]
	v_min_u32_e32 v190, 1, v190
	v_or_b32_e32 v190, v191, v190
	v_cvt_f32_u32_e32 v190, v190
	v_sub_u32_e32 v194, 32, v194
	v_ldexp_f32 v190, v190, v194
	v_fmamk_f32 v190, v190, 0x30800000, v223
	v_rsq_f32_e32 v190, v190
	v_mov_b32_e32 v172, v176
	v_mov_b32_e32 v173, v178
	v_mov_b32_e32 v236, v180
	v_mov_b32_e32 v237, v182
	v_mov_b32_e32 v238, v184
	v_mov_b32_e32 v239, v186
	v_mov_b32_e32 v230, v188
	v_mov_b32_e32 v231, v190
	v_mov_b32_e32 v254, s61
	s_cselect_b64 s[40:41], -1, 0
	s_cmp_lg_u32 s10, 1
	s_cbranch_scc1 .LBB0_343
	s_barrier
.LBB0_343:
	v_lshl_add_u64 v[8:9], v[144:145], 0, v[168:169]
	v_mov_b32_e32 v129, v169
	v_lshl_add_u64 v[10:11], v[144:145], 0, v[128:129]
	v_mov_b32_e32 v133, v169
	s_add_i32 m0, s25, 0x18000
	v_lshl_add_u64 v[8:9], v[8:9], 0, s[92:93]
	v_lshl_add_u64 v[14:15], v[142:143], 0, v[132:133]
	v_mov_b32_e32 v131, v169
	s_waitcnt vmcnt(2)
	s_barrier
	global_load_lds_dwordx4 v[8:9], off
	v_lshl_add_u64 v[8:9], v[10:11], 0, s[92:93]
	s_add_i32 m0, s25, 0x1a000
	s_add_i32 s53, s25, 0x8000
	v_lshl_add_u64 v[16:17], v[142:143], 0, v[130:131]
	global_load_lds_dwordx4 v[8:9], off
	v_lshl_add_u64 v[8:9], v[14:15], 0, s[92:93]
	s_mov_b32 m0, s53
	s_add_i32 s54, s25, 0xa000
	v_lshl_add_u64 v[12:13], v[0:1], 0, v[168:169]
	global_load_lds_dwordx4 v[8:9], off
	v_lshl_add_u64 v[8:9], v[16:17], 0, s[92:93]
	s_mov_b32 m0, s54
	v_lshl_add_u64 v[0:1], v[0:1], 0, v[128:129]
	global_load_lds_dwordx4 v[8:9], off
	s_add_i32 m0, s25, 0x1c000
	v_lshl_add_u64 v[8:9], v[12:13], 0, s[92:93]
	global_load_lds_dwordx4 v[8:9], off
	v_lshl_add_u64 v[0:1], v[0:1], 0, s[92:93]
	s_add_i32 m0, s25, 0x1e000
	v_and_b32_e32 v18, 15, v170
	global_load_lds_dwordx4 v[0:1], off
	v_add_u32_e32 v0, v7, v5
	s_lshr_b32 s1, s1, 6
	v_and_b32_e32 v19, 48, v170
	v_lshlrev_b32_e32 v18, 6, v18
	v_lshlrev_b32_e32 v21, 2, v170
	s_lshl_b32 s9, s9, 12
	v_add_lshl_u32 v0, v0, v6, 1
	v_mov_b32_e32 v1, v169
	v_or_b32_e32 v20, v18, v19
	s_lshl_b32 s10, s10, 13
	v_and_b32_e32 v21, 32, v21
	s_and_b32 s9, s9, 0x3000
	s_waitcnt vmcnt(6)
	s_add_i32 s55, s1, -2
	v_lshl_add_u64 v[134:135], s[94:95], 0, v[0:1]
	v_add_u32_e32 v0, v4, v2
	v_bitop3_b32 v18, v18, v21, v19 bitop3:0x36
	v_bitop3_b32 v19, s10, v20, v21 bitop3:0xf6
	s_cmpk_lt_u32 s8, 0x100
	v_add_lshl_u32 v0, v0, v3, 1
	v_or_b32_e32 v149, s9, v18
	s_cselect_b64 s[42:43], -1, 0
	s_ashr_i32 s56, s6, 31
	s_mov_b32 s39, s95
	v_lshl_add_u64 v[136:137], s[94:95], 0, v[0:1]
	s_mov_b32 s57, 0
	v_add_u32_e32 v151, 0, v19
	s_barrier
	s_mov_b32 s101, 0
	s_branch .LBB0_346
